# compression MLP unit: weight loads software-pipelined (2 buffers x 4 k-steps, counted waits) and the 64 pos-bias partial loads batched instead of one L2 round trip each; top-k popcount test on the SAL
# speedup vs baseline: 1.0113x; 1.0063x over previous
.LBB0_270:
	s_or_b64 exec, exec, s[22:23]
	s_and_b64 s[18:19], s[20:21], exec
	s_mov_b32 s14, 0x5b00000
	s_cselect_b32 s16, s14, 0x5c00000
	v_mov_b32_e32 v6, 0
	v_lshl_add_u64 v[10:11], v[130:131], 0, s[16:17]
	s_mov_b64 s[22:23], 0
	v_mov_b32_e32 v0, v230
	v_mov_b32_e32 v16, v228
	v_mov_b32_e32 v7, v6
	v_mov_b32_e32 v8, v6
	v_mov_b32_e32 v9, v6
	v_mov_b32_e32 v2, v6
	v_mov_b32_e32 v3, v6
	v_mov_b32_e32 v4, v6
	v_mov_b32_e32 v5, v6
	s_waitcnt lgkmcnt(0)
	s_barrier
	v_and_b32_e32 v12, 0x70, v228
	v_add_u32_e32 v13, 16, v228
	v_and_b32_e32 v13, 0x70, v13
	v_xad_u32 v114, v128, v12, v230
	v_xad_u32 v115, v129, v12, v230
	v_xad_u32 v116, v128, v13, v230
	v_xad_u32 v117, v129, v13, v230
	s_mov_b64 s[22:23], 0x10000
	v_lshl_add_u64 v[14:15], v[10:11], 0, s[22:23]
	ds_read_b128 v[18:21], v114
	ds_read_b128 v[22:25], v115
	ds_read_b128 v[26:29], v114 offset:128
	ds_read_b128 v[30:33], v115 offset:128
	global_load_dwordx4 v[34:37], v[10:11], off
	global_load_dwordx4 v[38:41], v[14:15], off
	global_load_dwordx4 v[42:45], v[10:11], off offset:64
	global_load_dwordx4 v[46:49], v[14:15], off offset:64
	global_load_dwordx4 v[50:53], v[10:11], off offset:128
	global_load_dwordx4 v[54:57], v[14:15], off offset:128
	global_load_dwordx4 v[58:61], v[10:11], off offset:192
	global_load_dwordx4 v[62:65], v[14:15], off offset:192
	ds_read_b128 v[66:69], v114 offset:256
	ds_read_b128 v[70:73], v115 offset:256
	ds_read_b128 v[74:77], v114 offset:384
	ds_read_b128 v[78:81], v115 offset:384
	global_load_dwordx4 v[82:85], v[10:11], off offset:256
	global_load_dwordx4 v[86:89], v[14:15], off offset:256
	global_load_dwordx4 v[90:93], v[10:11], off offset:320
	global_load_dwordx4 v[94:97], v[14:15], off offset:320
	global_load_dwordx4 v[98:101], v[10:11], off offset:384
	global_load_dwordx4 v[102:105], v[14:15], off offset:384
	global_load_dwordx4 v[106:109], v[10:11], off offset:448
	global_load_dwordx4 v[110:113], v[14:15], off offset:448
	s_waitcnt vmcnt(14) lgkmcnt(7)
	v_mfma_f32_16x16x32_bf16 v[6:9], v[18:21], v[34:37], v[6:9]
	v_mfma_f32_16x16x32_bf16 v[2:5], v[18:21], v[38:41], v[2:5]
	s_waitcnt vmcnt(12) lgkmcnt(6)
	v_mfma_f32_16x16x32_bf16 v[6:9], v[22:25], v[42:45], v[6:9]
	v_mfma_f32_16x16x32_bf16 v[2:5], v[22:25], v[46:49], v[2:5]
	s_waitcnt vmcnt(10) lgkmcnt(5)
	v_mfma_f32_16x16x32_bf16 v[6:9], v[26:29], v[50:53], v[6:9]
	v_mfma_f32_16x16x32_bf16 v[2:5], v[26:29], v[54:57], v[2:5]
	s_waitcnt vmcnt(8) lgkmcnt(4)
	v_mfma_f32_16x16x32_bf16 v[6:9], v[30:33], v[58:61], v[6:9]
	v_mfma_f32_16x16x32_bf16 v[2:5], v[30:33], v[62:65], v[2:5]
	ds_read_b128 v[18:21], v114 offset:512
	ds_read_b128 v[22:25], v115 offset:512
	ds_read_b128 v[26:29], v114 offset:640
	ds_read_b128 v[30:33], v115 offset:640
	global_load_dwordx4 v[34:37], v[10:11], off offset:512
	global_load_dwordx4 v[38:41], v[14:15], off offset:512
	global_load_dwordx4 v[42:45], v[10:11], off offset:576
	global_load_dwordx4 v[46:49], v[14:15], off offset:576
	global_load_dwordx4 v[50:53], v[10:11], off offset:640
	global_load_dwordx4 v[54:57], v[14:15], off offset:640
	global_load_dwordx4 v[58:61], v[10:11], off offset:704
	global_load_dwordx4 v[62:65], v[14:15], off offset:704
	s_waitcnt vmcnt(14) lgkmcnt(7)
	v_mfma_f32_16x16x32_bf16 v[6:9], v[66:69], v[82:85], v[6:9]
	v_mfma_f32_16x16x32_bf16 v[2:5], v[66:69], v[86:89], v[2:5]
	s_waitcnt vmcnt(12) lgkmcnt(6)
	v_mfma_f32_16x16x32_bf16 v[6:9], v[70:73], v[90:93], v[6:9]
	v_mfma_f32_16x16x32_bf16 v[2:5], v[70:73], v[94:97], v[2:5]
	s_waitcnt vmcnt(10) lgkmcnt(5)
	v_mfma_f32_16x16x32_bf16 v[6:9], v[74:77], v[98:101], v[6:9]
	v_mfma_f32_16x16x32_bf16 v[2:5], v[74:77], v[102:105], v[2:5]
	s_waitcnt vmcnt(8) lgkmcnt(4)
	v_mfma_f32_16x16x32_bf16 v[6:9], v[78:81], v[106:109], v[6:9]
	v_mfma_f32_16x16x32_bf16 v[2:5], v[78:81], v[110:113], v[2:5]
	ds_read_b128 v[66:69], v114 offset:768
	ds_read_b128 v[70:73], v115 offset:768
	ds_read_b128 v[74:77], v114 offset:896
	ds_read_b128 v[78:81], v115 offset:896
	global_load_dwordx4 v[82:85], v[10:11], off offset:768
	global_load_dwordx4 v[86:89], v[14:15], off offset:768
	global_load_dwordx4 v[90:93], v[10:11], off offset:832
	global_load_dwordx4 v[94:97], v[14:15], off offset:832
	global_load_dwordx4 v[98:101], v[10:11], off offset:896
	global_load_dwordx4 v[102:105], v[14:15], off offset:896
	global_load_dwordx4 v[106:109], v[10:11], off offset:960
	global_load_dwordx4 v[110:113], v[14:15], off offset:960
	s_waitcnt vmcnt(14) lgkmcnt(7)
	v_mfma_f32_16x16x32_bf16 v[6:9], v[18:21], v[34:37], v[6:9]
	v_mfma_f32_16x16x32_bf16 v[2:5], v[18:21], v[38:41], v[2:5]
	s_waitcnt vmcnt(12) lgkmcnt(6)
	v_mfma_f32_16x16x32_bf16 v[6:9], v[22:25], v[42:45], v[6:9]
	v_mfma_f32_16x16x32_bf16 v[2:5], v[22:25], v[46:49], v[2:5]
	s_waitcnt vmcnt(10) lgkmcnt(5)
	v_mfma_f32_16x16x32_bf16 v[6:9], v[26:29], v[50:53], v[6:9]
	v_mfma_f32_16x16x32_bf16 v[2:5], v[26:29], v[54:57], v[2:5]
	s_waitcnt vmcnt(8) lgkmcnt(4)
	v_mfma_f32_16x16x32_bf16 v[6:9], v[30:33], v[58:61], v[6:9]
	v_mfma_f32_16x16x32_bf16 v[2:5], v[30:33], v[62:65], v[2:5]
	ds_read_b128 v[18:21], v114 offset:1024
	ds_read_b128 v[22:25], v115 offset:1024
	ds_read_b128 v[26:29], v114 offset:1152
	ds_read_b128 v[30:33], v115 offset:1152
	global_load_dwordx4 v[34:37], v[10:11], off offset:1024
	global_load_dwordx4 v[38:41], v[14:15], off offset:1024
	global_load_dwordx4 v[42:45], v[10:11], off offset:1088
	global_load_dwordx4 v[46:49], v[14:15], off offset:1088
	global_load_dwordx4 v[50:53], v[10:11], off offset:1152
	global_load_dwordx4 v[54:57], v[14:15], off offset:1152
	global_load_dwordx4 v[58:61], v[10:11], off offset:1216
	global_load_dwordx4 v[62:65], v[14:15], off offset:1216
	s_waitcnt vmcnt(14) lgkmcnt(7)
	v_mfma_f32_16x16x32_bf16 v[6:9], v[66:69], v[82:85], v[6:9]
	v_mfma_f32_16x16x32_bf16 v[2:5], v[66:69], v[86:89], v[2:5]
	s_waitcnt vmcnt(12) lgkmcnt(6)
	v_mfma_f32_16x16x32_bf16 v[6:9], v[70:73], v[90:93], v[6:9]
	v_mfma_f32_16x16x32_bf16 v[2:5], v[70:73], v[94:97], v[2:5]
	s_waitcnt vmcnt(10) lgkmcnt(5)
	v_mfma_f32_16x16x32_bf16 v[6:9], v[74:77], v[98:101], v[6:9]
	v_mfma_f32_16x16x32_bf16 v[2:5], v[74:77], v[102:105], v[2:5]
	s_waitcnt vmcnt(8) lgkmcnt(4)
	v_mfma_f32_16x16x32_bf16 v[6:9], v[78:81], v[106:109], v[6:9]
	v_mfma_f32_16x16x32_bf16 v[2:5], v[78:81], v[110:113], v[2:5]
	ds_read_b128 v[66:69], v114 offset:1280
	ds_read_b128 v[70:73], v115 offset:1280
	ds_read_b128 v[74:77], v114 offset:1408
	ds_read_b128 v[78:81], v115 offset:1408
	global_load_dwordx4 v[82:85], v[10:11], off offset:1280
	global_load_dwordx4 v[86:89], v[14:15], off offset:1280
	global_load_dwordx4 v[90:93], v[10:11], off offset:1344
	global_load_dwordx4 v[94:97], v[14:15], off offset:1344
	global_load_dwordx4 v[98:101], v[10:11], off offset:1408
	global_load_dwordx4 v[102:105], v[14:15], off offset:1408
	global_load_dwordx4 v[106:109], v[10:11], off offset:1472
	global_load_dwordx4 v[110:113], v[14:15], off offset:1472
	s_waitcnt vmcnt(14) lgkmcnt(7)
	v_mfma_f32_16x16x32_bf16 v[6:9], v[18:21], v[34:37], v[6:9]
	v_mfma_f32_16x16x32_bf16 v[2:5], v[18:21], v[38:41], v[2:5]
	s_waitcnt vmcnt(12) lgkmcnt(6)
	v_mfma_f32_16x16x32_bf16 v[6:9], v[22:25], v[42:45], v[6:9]
	v_mfma_f32_16x16x32_bf16 v[2:5], v[22:25], v[46:49], v[2:5]
	s_waitcnt vmcnt(10) lgkmcnt(5)
	v_mfma_f32_16x16x32_bf16 v[6:9], v[26:29], v[50:53], v[6:9]
	v_mfma_f32_16x16x32_bf16 v[2:5], v[26:29], v[54:57], v[2:5]
	s_waitcnt vmcnt(8) lgkmcnt(4)
	v_mfma_f32_16x16x32_bf16 v[6:9], v[30:33], v[58:61], v[6:9]
	v_mfma_f32_16x16x32_bf16 v[2:5], v[30:33], v[62:65], v[2:5]
	ds_read_b128 v[18:21], v114 offset:1536
	ds_read_b128 v[22:25], v115 offset:1536
	ds_read_b128 v[26:29], v114 offset:1664
	ds_read_b128 v[30:33], v115 offset:1664
	global_load_dwordx4 v[34:37], v[10:11], off offset:1536
	global_load_dwordx4 v[38:41], v[14:15], off offset:1536
	global_load_dwordx4 v[42:45], v[10:11], off offset:1600
	global_load_dwordx4 v[46:49], v[14:15], off offset:1600
	global_load_dwordx4 v[50:53], v[10:11], off offset:1664
	global_load_dwordx4 v[54:57], v[14:15], off offset:1664
	global_load_dwordx4 v[58:61], v[10:11], off offset:1728
	global_load_dwordx4 v[62:65], v[14:15], off offset:1728
	s_waitcnt vmcnt(14) lgkmcnt(7)
	v_mfma_f32_16x16x32_bf16 v[6:9], v[66:69], v[82:85], v[6:9]
	v_mfma_f32_16x16x32_bf16 v[2:5], v[66:69], v[86:89], v[2:5]
	s_waitcnt vmcnt(12) lgkmcnt(6)
	v_mfma_f32_16x16x32_bf16 v[6:9], v[70:73], v[90:93], v[6:9]
	v_mfma_f32_16x16x32_bf16 v[2:5], v[70:73], v[94:97], v[2:5]
	s_waitcnt vmcnt(10) lgkmcnt(5)
	v_mfma_f32_16x16x32_bf16 v[6:9], v[74:77], v[98:101], v[6:9]
	v_mfma_f32_16x16x32_bf16 v[2:5], v[74:77], v[102:105], v[2:5]
	s_waitcnt vmcnt(8) lgkmcnt(4)
	v_mfma_f32_16x16x32_bf16 v[6:9], v[78:81], v[106:109], v[6:9]
	v_mfma_f32_16x16x32_bf16 v[2:5], v[78:81], v[110:113], v[2:5]
	ds_read_b128 v[66:69], v114 offset:1792
	ds_read_b128 v[70:73], v115 offset:1792
	ds_read_b128 v[74:77], v114 offset:1920
	ds_read_b128 v[78:81], v115 offset:1920
	global_load_dwordx4 v[82:85], v[10:11], off offset:1792
	global_load_dwordx4 v[86:89], v[14:15], off offset:1792
	global_load_dwordx4 v[90:93], v[10:11], off offset:1856
	global_load_dwordx4 v[94:97], v[14:15], off offset:1856
	global_load_dwordx4 v[98:101], v[10:11], off offset:1920
	global_load_dwordx4 v[102:105], v[14:15], off offset:1920
	global_load_dwordx4 v[106:109], v[10:11], off offset:1984
	global_load_dwordx4 v[110:113], v[14:15], off offset:1984
	s_waitcnt vmcnt(14) lgkmcnt(7)
	v_mfma_f32_16x16x32_bf16 v[6:9], v[18:21], v[34:37], v[6:9]
	v_mfma_f32_16x16x32_bf16 v[2:5], v[18:21], v[38:41], v[2:5]
	s_waitcnt vmcnt(12) lgkmcnt(6)
	v_mfma_f32_16x16x32_bf16 v[6:9], v[22:25], v[42:45], v[6:9]
	v_mfma_f32_16x16x32_bf16 v[2:5], v[22:25], v[46:49], v[2:5]
	s_waitcnt vmcnt(10) lgkmcnt(5)
	v_mfma_f32_16x16x32_bf16 v[6:9], v[26:29], v[50:53], v[6:9]
	v_mfma_f32_16x16x32_bf16 v[2:5], v[26:29], v[54:57], v[2:5]
	s_waitcnt vmcnt(8) lgkmcnt(4)
	v_mfma_f32_16x16x32_bf16 v[6:9], v[30:33], v[58:61], v[6:9]
	v_mfma_f32_16x16x32_bf16 v[2:5], v[30:33], v[62:65], v[2:5]
	ds_read_b128 v[18:21], v116 offset:2048
	ds_read_b128 v[22:25], v117 offset:2048
	ds_read_b128 v[26:29], v116 offset:2176
	ds_read_b128 v[30:33], v117 offset:2176
	global_load_dwordx4 v[34:37], v[10:11], off offset:2048
	global_load_dwordx4 v[38:41], v[14:15], off offset:2048
	global_load_dwordx4 v[42:45], v[10:11], off offset:2112
	global_load_dwordx4 v[46:49], v[14:15], off offset:2112
	global_load_dwordx4 v[50:53], v[10:11], off offset:2176
	global_load_dwordx4 v[54:57], v[14:15], off offset:2176
	global_load_dwordx4 v[58:61], v[10:11], off offset:2240
	global_load_dwordx4 v[62:65], v[14:15], off offset:2240
	s_waitcnt vmcnt(14) lgkmcnt(7)
	v_mfma_f32_16x16x32_bf16 v[6:9], v[66:69], v[82:85], v[6:9]
	v_mfma_f32_16x16x32_bf16 v[2:5], v[66:69], v[86:89], v[2:5]
	s_waitcnt vmcnt(12) lgkmcnt(6)
	v_mfma_f32_16x16x32_bf16 v[6:9], v[70:73], v[90:93], v[6:9]
	v_mfma_f32_16x16x32_bf16 v[2:5], v[70:73], v[94:97], v[2:5]
	s_waitcnt vmcnt(10) lgkmcnt(5)
	v_mfma_f32_16x16x32_bf16 v[6:9], v[74:77], v[98:101], v[6:9]
	v_mfma_f32_16x16x32_bf16 v[2:5], v[74:77], v[102:105], v[2:5]
	s_waitcnt vmcnt(8) lgkmcnt(4)
	v_mfma_f32_16x16x32_bf16 v[6:9], v[78:81], v[106:109], v[6:9]
	v_mfma_f32_16x16x32_bf16 v[2:5], v[78:81], v[110:113], v[2:5]
	ds_read_b128 v[66:69], v116 offset:2304
	ds_read_b128 v[70:73], v117 offset:2304
	ds_read_b128 v[74:77], v116 offset:2432
	ds_read_b128 v[78:81], v117 offset:2432
	global_load_dwordx4 v[82:85], v[10:11], off offset:2304
	global_load_dwordx4 v[86:89], v[14:15], off offset:2304
	global_load_dwordx4 v[90:93], v[10:11], off offset:2368
	global_load_dwordx4 v[94:97], v[14:15], off offset:2368
	global_load_dwordx4 v[98:101], v[10:11], off offset:2432
	global_load_dwordx4 v[102:105], v[14:15], off offset:2432
	global_load_dwordx4 v[106:109], v[10:11], off offset:2496
	global_load_dwordx4 v[110:113], v[14:15], off offset:2496
	s_waitcnt vmcnt(14) lgkmcnt(7)
	v_mfma_f32_16x16x32_bf16 v[6:9], v[18:21], v[34:37], v[6:9]
	v_mfma_f32_16x16x32_bf16 v[2:5], v[18:21], v[38:41], v[2:5]
	s_waitcnt vmcnt(12) lgkmcnt(6)
	v_mfma_f32_16x16x32_bf16 v[6:9], v[22:25], v[42:45], v[6:9]
	v_mfma_f32_16x16x32_bf16 v[2:5], v[22:25], v[46:49], v[2:5]
	s_waitcnt vmcnt(10) lgkmcnt(5)
	v_mfma_f32_16x16x32_bf16 v[6:9], v[26:29], v[50:53], v[6:9]
	v_mfma_f32_16x16x32_bf16 v[2:5], v[26:29], v[54:57], v[2:5]
	s_waitcnt vmcnt(8) lgkmcnt(4)
	v_mfma_f32_16x16x32_bf16 v[6:9], v[30:33], v[58:61], v[6:9]
	v_mfma_f32_16x16x32_bf16 v[2:5], v[30:33], v[62:65], v[2:5]
	ds_read_b128 v[18:21], v116 offset:2560
	ds_read_b128 v[22:25], v117 offset:2560
	ds_read_b128 v[26:29], v116 offset:2688
	ds_read_b128 v[30:33], v117 offset:2688
	global_load_dwordx4 v[34:37], v[10:11], off offset:2560
	global_load_dwordx4 v[38:41], v[14:15], off offset:2560
	global_load_dwordx4 v[42:45], v[10:11], off offset:2624
	global_load_dwordx4 v[46:49], v[14:15], off offset:2624
	global_load_dwordx4 v[50:53], v[10:11], off offset:2688
	global_load_dwordx4 v[54:57], v[14:15], off offset:2688
	global_load_dwordx4 v[58:61], v[10:11], off offset:2752
	global_load_dwordx4 v[62:65], v[14:15], off offset:2752
	s_waitcnt vmcnt(14) lgkmcnt(7)
	v_mfma_f32_16x16x32_bf16 v[6:9], v[66:69], v[82:85], v[6:9]
	v_mfma_f32_16x16x32_bf16 v[2:5], v[66:69], v[86:89], v[2:5]
	s_waitcnt vmcnt(12) lgkmcnt(6)
	v_mfma_f32_16x16x32_bf16 v[6:9], v[70:73], v[90:93], v[6:9]
	v_mfma_f32_16x16x32_bf16 v[2:5], v[70:73], v[94:97], v[2:5]
	s_waitcnt vmcnt(10) lgkmcnt(5)
	v_mfma_f32_16x16x32_bf16 v[6:9], v[74:77], v[98:101], v[6:9]
	v_mfma_f32_16x16x32_bf16 v[2:5], v[74:77], v[102:105], v[2:5]
	s_waitcnt vmcnt(8) lgkmcnt(4)
	v_mfma_f32_16x16x32_bf16 v[6:9], v[78:81], v[106:109], v[6:9]
	v_mfma_f32_16x16x32_bf16 v[2:5], v[78:81], v[110:113], v[2:5]
	ds_read_b128 v[66:69], v116 offset:2816
	ds_read_b128 v[70:73], v117 offset:2816
	ds_read_b128 v[74:77], v116 offset:2944
	ds_read_b128 v[78:81], v117 offset:2944
	global_load_dwordx4 v[82:85], v[10:11], off offset:2816
	global_load_dwordx4 v[86:89], v[14:15], off offset:2816
	global_load_dwordx4 v[90:93], v[10:11], off offset:2880
	global_load_dwordx4 v[94:97], v[14:15], off offset:2880
	global_load_dwordx4 v[98:101], v[10:11], off offset:2944
	global_load_dwordx4 v[102:105], v[14:15], off offset:2944
	global_load_dwordx4 v[106:109], v[10:11], off offset:3008
	global_load_dwordx4 v[110:113], v[14:15], off offset:3008
	s_waitcnt vmcnt(14) lgkmcnt(7)
	v_mfma_f32_16x16x32_bf16 v[6:9], v[18:21], v[34:37], v[6:9]
	v_mfma_f32_16x16x32_bf16 v[2:5], v[18:21], v[38:41], v[2:5]
	s_waitcnt vmcnt(12) lgkmcnt(6)
	v_mfma_f32_16x16x32_bf16 v[6:9], v[22:25], v[42:45], v[6:9]
	v_mfma_f32_16x16x32_bf16 v[2:5], v[22:25], v[46:49], v[2:5]
	s_waitcnt vmcnt(10) lgkmcnt(5)
	v_mfma_f32_16x16x32_bf16 v[6:9], v[26:29], v[50:53], v[6:9]
	v_mfma_f32_16x16x32_bf16 v[2:5], v[26:29], v[54:57], v[2:5]
	s_waitcnt vmcnt(8) lgkmcnt(4)
	v_mfma_f32_16x16x32_bf16 v[6:9], v[30:33], v[58:61], v[6:9]
	v_mfma_f32_16x16x32_bf16 v[2:5], v[30:33], v[62:65], v[2:5]
	ds_read_b128 v[18:21], v116 offset:3072
	ds_read_b128 v[22:25], v117 offset:3072
	ds_read_b128 v[26:29], v116 offset:3200
	ds_read_b128 v[30:33], v117 offset:3200
	global_load_dwordx4 v[34:37], v[10:11], off offset:3072
	global_load_dwordx4 v[38:41], v[14:15], off offset:3072
	global_load_dwordx4 v[42:45], v[10:11], off offset:3136
	global_load_dwordx4 v[46:49], v[14:15], off offset:3136
	global_load_dwordx4 v[50:53], v[10:11], off offset:3200
	global_load_dwordx4 v[54:57], v[14:15], off offset:3200
	global_load_dwordx4 v[58:61], v[10:11], off offset:3264
	global_load_dwordx4 v[62:65], v[14:15], off offset:3264
	s_waitcnt vmcnt(14) lgkmcnt(7)
	v_mfma_f32_16x16x32_bf16 v[6:9], v[66:69], v[82:85], v[6:9]
	v_mfma_f32_16x16x32_bf16 v[2:5], v[66:69], v[86:89], v[2:5]
	s_waitcnt vmcnt(12) lgkmcnt(6)
	v_mfma_f32_16x16x32_bf16 v[6:9], v[70:73], v[90:93], v[6:9]
	v_mfma_f32_16x16x32_bf16 v[2:5], v[70:73], v[94:97], v[2:5]
	s_waitcnt vmcnt(10) lgkmcnt(5)
	v_mfma_f32_16x16x32_bf16 v[6:9], v[74:77], v[98:101], v[6:9]
	v_mfma_f32_16x16x32_bf16 v[2:5], v[74:77], v[102:105], v[2:5]
	s_waitcnt vmcnt(8) lgkmcnt(4)
	v_mfma_f32_16x16x32_bf16 v[6:9], v[78:81], v[106:109], v[6:9]
	v_mfma_f32_16x16x32_bf16 v[2:5], v[78:81], v[110:113], v[2:5]
	ds_read_b128 v[66:69], v116 offset:3328
	ds_read_b128 v[70:73], v117 offset:3328
	ds_read_b128 v[74:77], v116 offset:3456
	ds_read_b128 v[78:81], v117 offset:3456
	global_load_dwordx4 v[82:85], v[10:11], off offset:3328
	global_load_dwordx4 v[86:89], v[14:15], off offset:3328
	global_load_dwordx4 v[90:93], v[10:11], off offset:3392
	global_load_dwordx4 v[94:97], v[14:15], off offset:3392
	global_load_dwordx4 v[98:101], v[10:11], off offset:3456
	global_load_dwordx4 v[102:105], v[14:15], off offset:3456
	global_load_dwordx4 v[106:109], v[10:11], off offset:3520
	global_load_dwordx4 v[110:113], v[14:15], off offset:3520
	s_waitcnt vmcnt(14) lgkmcnt(7)
	v_mfma_f32_16x16x32_bf16 v[6:9], v[18:21], v[34:37], v[6:9]
	v_mfma_f32_16x16x32_bf16 v[2:5], v[18:21], v[38:41], v[2:5]
	s_waitcnt vmcnt(12) lgkmcnt(6)
	v_mfma_f32_16x16x32_bf16 v[6:9], v[22:25], v[42:45], v[6:9]
	v_mfma_f32_16x16x32_bf16 v[2:5], v[22:25], v[46:49], v[2:5]
	s_waitcnt vmcnt(10) lgkmcnt(5)
	v_mfma_f32_16x16x32_bf16 v[6:9], v[26:29], v[50:53], v[6:9]
	v_mfma_f32_16x16x32_bf16 v[2:5], v[26:29], v[54:57], v[2:5]
	s_waitcnt vmcnt(8) lgkmcnt(4)
	v_mfma_f32_16x16x32_bf16 v[6:9], v[30:33], v[58:61], v[6:9]
	v_mfma_f32_16x16x32_bf16 v[2:5], v[30:33], v[62:65], v[2:5]
	ds_read_b128 v[18:21], v116 offset:3584
	ds_read_b128 v[22:25], v117 offset:3584
	ds_read_b128 v[26:29], v116 offset:3712
	ds_read_b128 v[30:33], v117 offset:3712
	global_load_dwordx4 v[34:37], v[10:11], off offset:3584
	global_load_dwordx4 v[38:41], v[14:15], off offset:3584
	global_load_dwordx4 v[42:45], v[10:11], off offset:3648
	global_load_dwordx4 v[46:49], v[14:15], off offset:3648
	global_load_dwordx4 v[50:53], v[10:11], off offset:3712
	global_load_dwordx4 v[54:57], v[14:15], off offset:3712
	global_load_dwordx4 v[58:61], v[10:11], off offset:3776
	global_load_dwordx4 v[62:65], v[14:15], off offset:3776
	s_waitcnt vmcnt(14) lgkmcnt(7)
	v_mfma_f32_16x16x32_bf16 v[6:9], v[66:69], v[82:85], v[6:9]
	v_mfma_f32_16x16x32_bf16 v[2:5], v[66:69], v[86:89], v[2:5]
	s_waitcnt vmcnt(12) lgkmcnt(6)
	v_mfma_f32_16x16x32_bf16 v[6:9], v[70:73], v[90:93], v[6:9]
	v_mfma_f32_16x16x32_bf16 v[2:5], v[70:73], v[94:97], v[2:5]
	s_waitcnt vmcnt(10) lgkmcnt(5)
	v_mfma_f32_16x16x32_bf16 v[6:9], v[74:77], v[98:101], v[6:9]
	v_mfma_f32_16x16x32_bf16 v[2:5], v[74:77], v[102:105], v[2:5]
	s_waitcnt vmcnt(8) lgkmcnt(4)
	v_mfma_f32_16x16x32_bf16 v[6:9], v[78:81], v[106:109], v[6:9]
	v_mfma_f32_16x16x32_bf16 v[2:5], v[78:81], v[110:113], v[2:5]
	ds_read_b128 v[66:69], v116 offset:3840
	ds_read_b128 v[70:73], v117 offset:3840
	ds_read_b128 v[74:77], v116 offset:3968
	ds_read_b128 v[78:81], v117 offset:3968
	global_load_dwordx4 v[82:85], v[10:11], off offset:3840
	global_load_dwordx4 v[86:89], v[14:15], off offset:3840
	global_load_dwordx4 v[90:93], v[10:11], off offset:3904
	global_load_dwordx4 v[94:97], v[14:15], off offset:3904
	global_load_dwordx4 v[98:101], v[10:11], off offset:3968
	global_load_dwordx4 v[102:105], v[14:15], off offset:3968
	global_load_dwordx4 v[106:109], v[10:11], off offset:4032
	global_load_dwordx4 v[110:113], v[14:15], off offset:4032
	s_waitcnt vmcnt(14) lgkmcnt(7)
	v_mfma_f32_16x16x32_bf16 v[6:9], v[18:21], v[34:37], v[6:9]
	v_mfma_f32_16x16x32_bf16 v[2:5], v[18:21], v[38:41], v[2:5]
	s_waitcnt vmcnt(12) lgkmcnt(6)
	v_mfma_f32_16x16x32_bf16 v[6:9], v[22:25], v[42:45], v[6:9]
	v_mfma_f32_16x16x32_bf16 v[2:5], v[22:25], v[46:49], v[2:5]
	s_waitcnt vmcnt(10) lgkmcnt(5)
	v_mfma_f32_16x16x32_bf16 v[6:9], v[26:29], v[50:53], v[6:9]
	v_mfma_f32_16x16x32_bf16 v[2:5], v[26:29], v[54:57], v[2:5]
	s_waitcnt vmcnt(8) lgkmcnt(4)
	v_mfma_f32_16x16x32_bf16 v[6:9], v[30:33], v[58:61], v[6:9]
	v_mfma_f32_16x16x32_bf16 v[2:5], v[30:33], v[62:65], v[2:5]
	s_waitcnt vmcnt(6) lgkmcnt(3)
	v_mfma_f32_16x16x32_bf16 v[6:9], v[66:69], v[82:85], v[6:9]
	v_mfma_f32_16x16x32_bf16 v[2:5], v[66:69], v[86:89], v[2:5]
	s_waitcnt vmcnt(4) lgkmcnt(2)
	v_mfma_f32_16x16x32_bf16 v[6:9], v[70:73], v[90:93], v[6:9]
	v_mfma_f32_16x16x32_bf16 v[2:5], v[70:73], v[94:97], v[2:5]
	s_waitcnt vmcnt(2) lgkmcnt(1)
	v_mfma_f32_16x16x32_bf16 v[6:9], v[74:77], v[98:101], v[6:9]
	v_mfma_f32_16x16x32_bf16 v[2:5], v[74:77], v[102:105], v[2:5]
	s_waitcnt vmcnt(0) lgkmcnt(0)
	v_mfma_f32_16x16x32_bf16 v[6:9], v[78:81], v[106:109], v[6:9]
	v_mfma_f32_16x16x32_bf16 v[2:5], v[78:81], v[110:113], v[2:5]
	s_lshl_b32 s14, s81, 6
	s_and_b32 s18, s14, 0xffffe000
	s_ashr_i32 s19, s18, 31
	v_lshl_add_u64 v[66:67], s[18:19], 2, v[142:143]
	s_mov_b64 s[18:19], 0x1000
	v_lshl_add_u64 v[68:69], v[66:67], 0, s[18:19]
	s_mov_b64 s[18:19], 0x2000
	v_lshl_add_u64 v[70:71], v[66:67], 0, s[18:19]
	s_mov_b64 s[18:19], 0x3000
	v_lshl_add_u64 v[72:73], v[66:67], 0, s[18:19]
	s_mov_b64 s[18:19], 0x4000
	v_lshl_add_u64 v[74:75], v[66:67], 0, s[18:19]
	s_mov_b64 s[18:19], 0x5000
	v_lshl_add_u64 v[76:77], v[66:67], 0, s[18:19]
	s_mov_b64 s[18:19], 0x6000
	v_lshl_add_u64 v[78:79], v[66:67], 0, s[18:19]
	s_mov_b64 s[18:19], 0x7000
	v_lshl_add_u64 v[80:81], v[66:67], 0, s[18:19]
	global_load_dword v30, v[66:67], off
	global_load_dword v31, v[66:67], off offset:1024
	global_load_dword v32, v[66:67], off offset:2048
	global_load_dword v33, v[66:67], off offset:3072
	global_load_dword v34, v[68:69], off
	global_load_dword v35, v[68:69], off offset:1024
	global_load_dword v36, v[68:69], off offset:2048
	global_load_dword v37, v[68:69], off offset:3072
	global_load_dword v38, v[70:71], off
	global_load_dword v39, v[70:71], off offset:1024
	global_load_dword v40, v[70:71], off offset:2048
	global_load_dword v41, v[70:71], off offset:3072
	global_load_dword v42, v[72:73], off
	global_load_dword v43, v[72:73], off offset:1024
	global_load_dword v44, v[72:73], off offset:2048
	global_load_dword v45, v[72:73], off offset:3072
	global_load_dword v46, v[74:75], off
	global_load_dword v47, v[74:75], off offset:1024
	global_load_dword v48, v[74:75], off offset:2048
	global_load_dword v49, v[74:75], off offset:3072
	global_load_dword v50, v[76:77], off
	global_load_dword v51, v[76:77], off offset:1024
	global_load_dword v52, v[76:77], off offset:2048
	global_load_dword v53, v[76:77], off offset:3072
	global_load_dword v54, v[78:79], off
	global_load_dword v55, v[78:79], off offset:1024
	global_load_dword v56, v[78:79], off offset:2048
	global_load_dword v57, v[78:79], off offset:3072
	global_load_dword v58, v[80:81], off
	global_load_dword v59, v[80:81], off offset:1024
	global_load_dword v60, v[80:81], off offset:2048
	global_load_dword v61, v[80:81], off offset:3072
	global_load_dword v82, v[66:67], off offset:64
	global_load_dword v83, v[66:67], off offset:1088
	global_load_dword v84, v[66:67], off offset:2112
	global_load_dword v85, v[66:67], off offset:3136
	global_load_dword v86, v[68:69], off offset:64
	global_load_dword v87, v[68:69], off offset:1088
	global_load_dword v88, v[68:69], off offset:2112
	global_load_dword v89, v[68:69], off offset:3136
	global_load_dword v90, v[70:71], off offset:64
	global_load_dword v91, v[70:71], off offset:1088
	global_load_dword v92, v[70:71], off offset:2112
	global_load_dword v93, v[70:71], off offset:3136
	global_load_dword v94, v[72:73], off offset:64
	global_load_dword v95, v[72:73], off offset:1088
	global_load_dword v96, v[72:73], off offset:2112
	global_load_dword v97, v[72:73], off offset:3136
	s_waitcnt vmcnt(47)
	v_add_f32_e32 v0, 0, v30
	s_waitcnt vmcnt(46)
	v_add_f32_e32 v0, v0, v31
	s_waitcnt vmcnt(45)
	v_add_f32_e32 v0, v0, v32
	s_waitcnt vmcnt(44)
	v_add_f32_e32 v0, v0, v33
	s_waitcnt vmcnt(43)
	v_add_f32_e32 v0, v0, v34
	s_waitcnt vmcnt(42)
	v_add_f32_e32 v0, v0, v35
	s_waitcnt vmcnt(41)
	v_add_f32_e32 v0, v0, v36
	s_waitcnt vmcnt(40)
	v_add_f32_e32 v0, v0, v37
	s_waitcnt vmcnt(39)
	v_add_f32_e32 v0, v0, v38
	s_waitcnt vmcnt(38)
	v_add_f32_e32 v0, v0, v39
	s_waitcnt vmcnt(37)
	v_add_f32_e32 v0, v0, v40
	s_waitcnt vmcnt(36)
	v_add_f32_e32 v0, v0, v41
	s_waitcnt vmcnt(35)
	v_add_f32_e32 v0, v0, v42
	s_waitcnt vmcnt(34)
	v_add_f32_e32 v0, v0, v43
	s_waitcnt vmcnt(33)
	v_add_f32_e32 v0, v0, v44
	s_waitcnt vmcnt(32)
	v_add_f32_e32 v0, v0, v45
	s_waitcnt vmcnt(31)
	v_add_f32_e32 v0, v0, v46
	s_waitcnt vmcnt(30)
	v_add_f32_e32 v0, v0, v47
	s_waitcnt vmcnt(29)
	v_add_f32_e32 v0, v0, v48
	s_waitcnt vmcnt(28)
	v_add_f32_e32 v0, v0, v49
	s_waitcnt vmcnt(27)
	v_add_f32_e32 v0, v0, v50
	s_waitcnt vmcnt(26)
	v_add_f32_e32 v0, v0, v51
	s_waitcnt vmcnt(25)
	v_add_f32_e32 v0, v0, v52
	s_waitcnt vmcnt(24)
	v_add_f32_e32 v0, v0, v53
	s_waitcnt vmcnt(23)
	v_add_f32_e32 v0, v0, v54
	s_waitcnt vmcnt(22)
	v_add_f32_e32 v0, v0, v55
	s_waitcnt vmcnt(21)
	v_add_f32_e32 v0, v0, v56
	s_waitcnt vmcnt(20)
	v_add_f32_e32 v0, v0, v57
	s_waitcnt vmcnt(19)
	v_add_f32_e32 v0, v0, v58
	s_waitcnt vmcnt(18)
	v_add_f32_e32 v0, v0, v59
	s_waitcnt vmcnt(17)
	v_add_f32_e32 v0, v0, v60
	s_waitcnt vmcnt(16)
	v_add_f32_e32 v0, v0, v61
	global_load_dword v98, v[74:75], off offset:64
	global_load_dword v99, v[74:75], off offset:1088
	global_load_dword v100, v[74:75], off offset:2112
	global_load_dword v101, v[74:75], off offset:3136
	global_load_dword v102, v[76:77], off offset:64
	global_load_dword v103, v[76:77], off offset:1088
	global_load_dword v104, v[76:77], off offset:2112
	global_load_dword v105, v[76:77], off offset:3136
	global_load_dword v106, v[78:79], off offset:64
	global_load_dword v107, v[78:79], off offset:1088
	global_load_dword v108, v[78:79], off offset:2112
	global_load_dword v109, v[78:79], off offset:3136
	global_load_dword v110, v[80:81], off offset:64
	global_load_dword v111, v[80:81], off offset:1088
	global_load_dword v112, v[80:81], off offset:2112
	global_load_dword v113, v[80:81], off offset:3136
	v_add_f32_e32 v6, v6, v0
	v_mul_f32_e32 v26, 0x3d372713, v6
	v_mul_f32_e32 v26, v6, v26
	v_fma_f32 v26, v6, v26, v6
	v_mul_f32_e32 v26, 0x3f4c422a, v26
	v_add_f32_e32 v26, v26, v26
	v_mul_f32_e32 v26, 0x3fb8aa3b, v26
	v_exp_f32_e32 v26, v26
	v_mul_f32_e32 v6, 0.5, v6
	v_add_f32_e32 v26, 1.0, v26
	v_div_scale_f32 v27, s[18:19], v26, v26, 2.0
	v_rcp_f32_e32 v28, v27
	s_nop 0
	v_fma_f32 v29, -v27, v28, 1.0
	v_fmac_f32_e32 v28, v29, v28
	v_div_scale_f32 v29, vcc, 2.0, v26, 2.0
	v_mul_f32_e32 v30, v29, v28
	v_fma_f32 v31, -v27, v30, v29
	v_fmac_f32_e32 v30, v31, v28
	v_fma_f32 v27, -v27, v30, v29
	v_div_fmas_f32 v27, v27, v28, v30
	v_div_fixup_f32 v26, v27, v26, 2.0
	v_sub_f32_e32 v26, 1.0, v26
	v_add_f32_e32 v26, 1.0, v26
	v_mul_f32_e32 v6, v6, v26
	v_cvt_pk_bf16_f32 v6, v6, s0
	ds_write_b16 v231, v6 offset:36864
	v_add_f32_e32 v6, v7, v0
	v_mul_f32_e32 v7, 0x3d372713, v6
	v_mul_f32_e32 v7, v6, v7
	v_fma_f32 v7, v6, v7, v6
	v_mul_f32_e32 v7, 0x3f4c422a, v7
	v_add_f32_e32 v7, v7, v7
	v_mul_f32_e32 v7, 0x3fb8aa3b, v7
	v_exp_f32_e32 v7, v7
	v_mul_f32_e32 v6, 0.5, v6
	v_add_f32_e32 v7, 1.0, v7
	v_div_scale_f32 v26, s[18:19], v7, v7, 2.0
	v_rcp_f32_e32 v27, v26
	s_nop 0
	v_fma_f32 v28, -v26, v27, 1.0
	v_fmac_f32_e32 v27, v28, v27
	v_div_scale_f32 v28, vcc, 2.0, v7, 2.0
	v_mul_f32_e32 v29, v28, v27
	v_fma_f32 v30, -v26, v29, v28
	v_fmac_f32_e32 v29, v30, v27
	v_fma_f32 v26, -v26, v29, v28
	v_div_fmas_f32 v26, v26, v27, v29
	v_div_fixup_f32 v7, v26, v7, 2.0
	v_sub_f32_e32 v7, 1.0, v7
	v_add_f32_e32 v7, 1.0, v7
	v_mul_f32_e32 v6, v6, v7
	v_cvt_pk_bf16_f32 v6, v6, s0
	ds_write_b16 v231, v6 offset:37392
	v_add_f32_e32 v6, v8, v0
	v_mul_f32_e32 v7, 0x3d372713, v6
	v_mul_f32_e32 v7, v6, v7
	v_fma_f32 v7, v6, v7, v6
	v_mul_f32_e32 v7, 0x3f4c422a, v7
	v_add_f32_e32 v7, v7, v7
	v_mul_f32_e32 v7, 0x3fb8aa3b, v7
	v_exp_f32_e32 v7, v7
	v_mul_f32_e32 v6, 0.5, v6
	v_add_f32_e32 v0, v9, v0
	v_add_f32_e32 v7, 1.0, v7
	v_div_scale_f32 v8, s[18:19], v7, v7, 2.0
	v_rcp_f32_e32 v26, v8
	s_nop 0
	v_fma_f32 v27, -v8, v26, 1.0
	v_fmac_f32_e32 v26, v27, v26
	v_div_scale_f32 v27, vcc, 2.0, v7, 2.0
	v_mul_f32_e32 v28, v27, v26
	v_fma_f32 v29, -v8, v28, v27
	v_fmac_f32_e32 v28, v29, v26
	v_fma_f32 v8, -v8, v28, v27
	v_div_fmas_f32 v8, v8, v26, v28
	v_div_fixup_f32 v7, v8, v7, 2.0
	v_sub_f32_e32 v7, 1.0, v7
	v_add_f32_e32 v7, 1.0, v7
	v_mul_f32_e32 v6, v6, v7
	v_cvt_pk_bf16_f32 v6, v6, s0
	ds_write_b16 v231, v6 offset:37920
	v_mul_f32_e32 v6, 0x3d372713, v0
	v_mul_f32_e32 v6, v0, v6
	v_fma_f32 v6, v0, v6, v0
	v_mul_f32_e32 v6, 0x3f4c422a, v6
	v_add_f32_e32 v6, v6, v6
	v_mul_f32_e32 v6, 0x3fb8aa3b, v6
	v_exp_f32_e32 v6, v6
	v_mul_f32_e32 v0, 0.5, v0
	v_add_f32_e32 v6, 1.0, v6
	v_div_scale_f32 v7, s[18:19], v6, v6, 2.0
	v_rcp_f32_e32 v8, v7
	s_nop 0
	v_fma_f32 v9, -v7, v8, 1.0
	v_fmac_f32_e32 v8, v9, v8
	v_div_scale_f32 v9, vcc, 2.0, v6, 2.0
	v_mul_f32_e32 v26, v9, v8
	v_fma_f32 v27, -v7, v26, v9
	v_fmac_f32_e32 v26, v27, v8
	v_fma_f32 v7, -v7, v26, v9
	v_div_fmas_f32 v7, v7, v8, v26
	v_div_fixup_f32 v6, v7, v6, 2.0
	v_sub_f32_e32 v6, 1.0, v6
	v_add_f32_e32 v6, 1.0, v6
	v_mul_f32_e32 v0, v0, v6
	v_cvt_pk_bf16_f32 v0, v0, s0
	ds_write_b16 v231, v0 offset:38448
	s_waitcnt vmcnt(31)
	v_add_f32_e32 v0, 0, v82
	s_waitcnt vmcnt(30)
	v_add_f32_e32 v0, v0, v83
	s_waitcnt vmcnt(29)
	v_add_f32_e32 v0, v0, v84
	s_waitcnt vmcnt(28)
	v_add_f32_e32 v0, v0, v85
	s_waitcnt vmcnt(27)
	v_add_f32_e32 v0, v0, v86
	s_waitcnt vmcnt(26)
	v_add_f32_e32 v0, v0, v87
	s_waitcnt vmcnt(25)
	v_add_f32_e32 v0, v0, v88
	s_waitcnt vmcnt(24)
	v_add_f32_e32 v0, v0, v89
	s_waitcnt vmcnt(23)
	v_add_f32_e32 v0, v0, v90
	s_waitcnt vmcnt(22)
	v_add_f32_e32 v0, v0, v91
	s_waitcnt vmcnt(21)
	v_add_f32_e32 v0, v0, v92
	s_waitcnt vmcnt(20)
	v_add_f32_e32 v0, v0, v93
	s_waitcnt vmcnt(19)
	v_add_f32_e32 v0, v0, v94
	s_waitcnt vmcnt(18)
	v_add_f32_e32 v0, v0, v95
	s_waitcnt vmcnt(17)
	v_add_f32_e32 v0, v0, v96
	s_waitcnt vmcnt(16)
	v_add_f32_e32 v0, v0, v97
	s_waitcnt vmcnt(15)
	v_add_f32_e32 v0, v0, v98
	s_waitcnt vmcnt(14)
	v_add_f32_e32 v0, v0, v99
	s_waitcnt vmcnt(13)
	v_add_f32_e32 v0, v0, v100
	s_waitcnt vmcnt(12)
	v_add_f32_e32 v0, v0, v101
	s_waitcnt vmcnt(11)
	v_add_f32_e32 v0, v0, v102
	s_waitcnt vmcnt(10)
	v_add_f32_e32 v0, v0, v103
	s_waitcnt vmcnt(9)
	v_add_f32_e32 v0, v0, v104
	s_waitcnt vmcnt(8)
	v_add_f32_e32 v0, v0, v105
	s_waitcnt vmcnt(7)
	v_add_f32_e32 v0, v0, v106
	s_waitcnt vmcnt(6)
	v_add_f32_e32 v0, v0, v107
	s_waitcnt vmcnt(5)
	v_add_f32_e32 v0, v0, v108
	s_waitcnt vmcnt(4)
	v_add_f32_e32 v0, v0, v109
	s_waitcnt vmcnt(3)
	v_add_f32_e32 v0, v0, v110
	s_waitcnt vmcnt(2)
	v_add_f32_e32 v0, v0, v111
	s_waitcnt vmcnt(1)
	v_add_f32_e32 v0, v0, v112
	s_waitcnt vmcnt(0)
	v_add_f32_e32 v0, v0, v113
	v_add_f32_e32 v2, v2, v0
	v_mul_f32_e32 v6, 0x3d372713, v2
	v_mul_f32_e32 v6, v2, v6
	v_fma_f32 v6, v2, v6, v2
	v_mul_f32_e32 v6, 0x3f4c422a, v6
	v_add_f32_e32 v6, v6, v6
	v_mul_f32_e32 v6, 0x3fb8aa3b, v6
	v_exp_f32_e32 v6, v6
	v_mul_f32_e32 v2, 0.5, v2
	v_add_f32_e32 v6, 1.0, v6
	v_div_scale_f32 v7, s[18:19], v6, v6, 2.0
	v_rcp_f32_e32 v8, v7
	s_nop 0
	v_fma_f32 v9, -v7, v8, 1.0
	v_fmac_f32_e32 v8, v9, v8
	v_div_scale_f32 v9, vcc, 2.0, v6, 2.0
	v_mul_f32_e32 v10, v9, v8
	v_fma_f32 v11, -v7, v10, v9
	v_fmac_f32_e32 v10, v11, v8
	v_fma_f32 v7, -v7, v10, v9
	v_div_fmas_f32 v7, v7, v8, v10
	v_div_fixup_f32 v6, v7, v6, 2.0
	v_sub_f32_e32 v6, 1.0, v6
	v_add_f32_e32 v6, 1.0, v6
	v_mul_f32_e32 v2, v2, v6
	v_cvt_pk_bf16_f32 v2, v2, s0
	ds_write_b16 v231, v2 offset:36896
	v_add_f32_e32 v2, v3, v0
	v_mul_f32_e32 v3, 0x3d372713, v2
	v_mul_f32_e32 v3, v2, v3
	v_fma_f32 v3, v2, v3, v2
	v_mul_f32_e32 v3, 0x3f4c422a, v3
	v_add_f32_e32 v3, v3, v3
	v_mul_f32_e32 v3, 0x3fb8aa3b, v3
	v_exp_f32_e32 v3, v3
	v_mul_f32_e32 v2, 0.5, v2
	v_add_f32_e32 v3, 1.0, v3
	v_div_scale_f32 v6, s[18:19], v3, v3, 2.0
	v_rcp_f32_e32 v7, v6
	s_nop 0
	v_fma_f32 v8, -v6, v7, 1.0
	v_fmac_f32_e32 v7, v8, v7
	v_div_scale_f32 v8, vcc, 2.0, v3, 2.0
	v_mul_f32_e32 v9, v8, v7
	v_fma_f32 v10, -v6, v9, v8
	v_fmac_f32_e32 v9, v10, v7
	v_fma_f32 v6, -v6, v9, v8
	v_div_fmas_f32 v6, v6, v7, v9
	v_div_fixup_f32 v3, v6, v3, 2.0
	v_sub_f32_e32 v3, 1.0, v3
	v_add_f32_e32 v3, 1.0, v3
	v_mul_f32_e32 v2, v2, v3
	v_cvt_pk_bf16_f32 v2, v2, s0
	ds_write_b16 v231, v2 offset:37424
	v_add_f32_e32 v2, v4, v0
	v_mul_f32_e32 v3, 0x3d372713, v2
	v_mul_f32_e32 v3, v2, v3
	v_fma_f32 v3, v2, v3, v2
	v_mul_f32_e32 v3, 0x3f4c422a, v3
	v_add_f32_e32 v3, v3, v3
	v_mul_f32_e32 v3, 0x3fb8aa3b, v3
	v_exp_f32_e32 v3, v3
	v_mul_f32_e32 v2, 0.5, v2
	v_add_f32_e32 v0, v5, v0
	v_add_f32_e32 v3, 1.0, v3
	v_div_scale_f32 v4, s[18:19], v3, v3, 2.0
	v_rcp_f32_e32 v6, v4
	s_nop 0
	v_fma_f32 v7, -v4, v6, 1.0
	v_fmac_f32_e32 v6, v7, v6
	v_div_scale_f32 v7, vcc, 2.0, v3, 2.0
	v_mul_f32_e32 v8, v7, v6
	v_fma_f32 v9, -v4, v8, v7
	v_fmac_f32_e32 v8, v9, v6
	v_fma_f32 v4, -v4, v8, v7
	v_div_fmas_f32 v4, v4, v6, v8
	v_div_fixup_f32 v3, v4, v3, 2.0
	v_sub_f32_e32 v3, 1.0, v3
	v_add_f32_e32 v3, 1.0, v3
	v_mul_f32_e32 v2, v2, v3
	v_cvt_pk_bf16_f32 v2, v2, s0
	ds_write_b16 v231, v2 offset:37952
	v_mul_f32_e32 v2, 0x3d372713, v0
	v_mul_f32_e32 v2, v0, v2
	v_fma_f32 v2, v0, v2, v0
	v_mul_f32_e32 v2, 0x3f4c422a, v2
	v_add_f32_e32 v2, v2, v2
	v_mul_f32_e32 v2, 0x3fb8aa3b, v2
	v_exp_f32_e32 v2, v2
	v_mul_f32_e32 v0, 0.5, v0
	v_add_f32_e32 v2, 1.0, v2
	v_div_scale_f32 v3, s[18:19], v2, v2, 2.0
	v_rcp_f32_e32 v4, v3
	s_nop 0
	v_fma_f32 v5, -v3, v4, 1.0
	v_fmac_f32_e32 v4, v5, v4
	v_div_scale_f32 v5, vcc, 2.0, v2, 2.0
	v_mul_f32_e32 v6, v5, v4
	v_fma_f32 v7, -v3, v6, v5
	v_fmac_f32_e32 v6, v7, v4
	v_fma_f32 v3, -v3, v6, v5
	v_div_fmas_f32 v3, v3, v4, v6
	v_div_fixup_f32 v2, v3, v2, 2.0
	v_sub_f32_e32 v2, 1.0, v2
	v_add_f32_e32 v2, 1.0, v2
	v_mul_f32_e32 v0, v0, v2
	v_cvt_pk_bf16_f32 v0, v0, s0
	s_and_b64 vcc, exec, s[10:11]
	ds_write_b16 v231, v0 offset:38480
	s_waitcnt lgkmcnt(0)
	s_barrier
	s_cbranch_vccz .LBB0_274
	s_and_b64 s[18:19], s[20:21], exec
	s_mov_b32 s14, 0x5d00000
	s_cselect_b32 s16, s14, 0x5d10000
	v_lshl_add_u64 v[14:15], v[132:133], 0, s[16:17]
	global_load_dwordx4 v[6:9], v[14:15], off
	global_load_dwordx4 v[10:13], v[14:15], off offset:64
	ds_read_b128 v[2:5], v229 offset:36864
	s_mov_b32 s14, 0x5e00000
	s_cselect_b32 s20, s14, 0x5e40000
	s_mov_b32 s21, s17
	s_lshl_b32 s4, s4, 15
	s_waitcnt vmcnt(1) lgkmcnt(0)
	v_mfma_f32_16x16x32_bf16 v[2:5], v[2:5], v[6:9], 0
	ds_read_b128 v[6:9], v229 offset:36928
	s_waitcnt vmcnt(0) lgkmcnt(0)
	v_mfma_f32_16x16x32_bf16 v[2:5], v[6:9], v[10:13], v[2:5]
	global_load_dwordx4 v[10:13], v[14:15], off offset:128
	ds_read_b128 v[6:9], v229 offset:36992
	s_waitcnt vmcnt(0) lgkmcnt(0)
	v_mfma_f32_16x16x32_bf16 v[2:5], v[6:9], v[10:13], v[2:5]
	global_load_dwordx4 v[10:13], v[14:15], off offset:192
	ds_read_b128 v[6:9], v229 offset:37056
	s_waitcnt vmcnt(0) lgkmcnt(0)
	v_mfma_f32_16x16x32_bf16 v[2:5], v[6:9], v[10:13], v[2:5]
	global_load_dwordx4 v[10:13], v[14:15], off offset:256
	ds_read_b128 v[6:9], v229 offset:37120
	s_waitcnt vmcnt(0) lgkmcnt(0)
	v_mfma_f32_16x16x32_bf16 v[2:5], v[6:9], v[10:13], v[2:5]
	global_load_dwordx4 v[10:13], v[14:15], off offset:320
	ds_read_b128 v[6:9], v229 offset:37184
	s_waitcnt vmcnt(0) lgkmcnt(0)
	v_mfma_f32_16x16x32_bf16 v[2:5], v[6:9], v[10:13], v[2:5]
	global_load_dwordx4 v[10:13], v[14:15], off offset:384
	ds_read_b128 v[6:9], v229 offset:37248
	s_waitcnt vmcnt(0) lgkmcnt(0)
	v_mfma_f32_16x16x32_bf16 v[2:5], v[6:9], v[10:13], v[2:5]
	global_load_dwordx4 v[10:13], v[14:15], off offset:448
	ds_read_b128 v[6:9], v229 offset:37312
	s_waitcnt vmcnt(0) lgkmcnt(0)
	v_mfma_f32_16x16x32_bf16 v[2:5], v[6:9], v[10:13], v[2:5]
	v_lshl_or_b32 v8, s5, 4, v216
	v_lshl_add_u64 v[6:7], v[134:135], 0, s[20:21]
	v_lshl_or_b32 v0, v8, 7, s4
	v_lshl_add_u64 v[6:7], v[6:7], 0, v[0:1]
	s_nop 3
	v_cvt_pk_bf16_f32 v0, v3, s0
	global_store_short v[6:7], v0, off offset:128
	v_cvt_pk_bf16_f32 v0, v4, s0
	s_movk_i32 s4, 0xfc
	global_store_short v[6:7], v0, off offset:256
	v_cvt_pk_bf16_f32 v0, v5, s0
	v_cmp_ne_u32_e32 vcc, s4, v8
	v_cvt_pk_bf16_f32 v2, v2, s0
	global_store_short v[6:7], v2, off
	v_cndmask_b32_e32 v0, 0, v0, vcc
	global_store_short v[6:7], v0, off offset:384

.LBB0_404:
	ds_read2st64_b32 v[18:19], v0 offset1:64
	s_mov_b64 s[22:23], s[8:9]
	s_waitcnt lgkmcnt(0)
	v_add_f32_e32 v20, v18, v19
	ds_read2st64_b32 v[18:19], v0 offset0:128 offset1:192
	s_waitcnt lgkmcnt(0)
	v_add_f32_e32 v18, v20, v18
	v_add_f32_e32 v18, v18, v19
	v_add_f32_e32 v19, 0x49742400, v18
	v_cndmask_b32_e32 v18, v18, v19, vcc
	v_cndmask_b32_e64 v18, v18, v148, s[42:43]
	v_not_b32_e32 v19, v18
	v_cmp_gt_i32_e64 s[6:7], 0, v18
	s_nop 1
	v_cndmask_b32_e64 v18, -|v18|, v19, s[6:7]
	v_cmp_gt_i32_e64 s[6:7], 0, v18
	s_bcnt1_i32_b64 s16, s[6:7]
	s_cmp_gt_u32 s16, 15
	s_cselect_b32 s10, 0x80000000, 0
	s_or_b32 s11, s10, 2.0
	v_cmp_le_u32_e64 s[6:7], s11, v18
	s_bcnt1_i32_b64 s16, s[6:7]
	s_cmp_gt_u32 s16, 15
	s_cselect_b32 s10, s11, s10
	s_or_b32 s11, s10, 0x20000000
	v_cmp_le_u32_e64 s[6:7], s11, v18
	s_bcnt1_i32_b64 s16, s[6:7]
	s_cmp_gt_u32 s16, 15
	s_cselect_b32 s10, s11, s10
	s_or_b32 s11, s10, 0x10000000
	v_cmp_le_u32_e64 s[6:7], s11, v18
	s_bcnt1_i32_b64 s16, s[6:7]
	s_cmp_gt_u32 s16, 15
	s_cselect_b32 s10, s11, s10
	s_or_b32 s11, s10, 0x8000000
	v_cmp_le_u32_e64 s[6:7], s11, v18
	s_bcnt1_i32_b64 s16, s[6:7]
	s_cmp_gt_u32 s16, 15
	s_cselect_b32 s10, s11, s10
	s_or_b32 s11, s10, 0x4000000
	v_cmp_le_u32_e64 s[6:7], s11, v18
	s_bcnt1_i32_b64 s16, s[6:7]
	s_cmp_gt_u32 s16, 15
	s_cselect_b32 s10, s11, s10
	s_or_b32 s11, s10, 0x2000000
	v_cmp_le_u32_e64 s[6:7], s11, v18
	s_bcnt1_i32_b64 s16, s[6:7]
	s_cmp_gt_u32 s16, 15
	s_cselect_b32 s10, s11, s10
	s_or_b32 s11, s10, 0x1000000
	v_cmp_le_u32_e64 s[6:7], s11, v18
	s_bcnt1_i32_b64 s16, s[6:7]
	s_cmp_gt_u32 s16, 15
	s_cselect_b32 s10, s11, s10
	s_or_b32 s11, s10, 0x800000
	v_cmp_le_u32_e64 s[6:7], s11, v18
	s_bcnt1_i32_b64 s16, s[6:7]
	s_cmp_gt_u32 s16, 15
	s_cselect_b32 s10, s11, s10
	s_or_b32 s11, s10, 0x400000
	v_cmp_le_u32_e64 s[6:7], s11, v18
	s_bcnt1_i32_b64 s16, s[6:7]
	s_cmp_gt_u32 s16, 15
	s_cselect_b32 s10, s11, s10
	s_or_b32 s11, s10, 0x200000
	v_cmp_le_u32_e64 s[6:7], s11, v18
	s_bcnt1_i32_b64 s16, s[6:7]
	s_cmp_gt_u32 s16, 15
	s_cselect_b32 s10, s11, s10
	s_or_b32 s11, s10, 0x100000
	v_cmp_le_u32_e64 s[6:7], s11, v18
	s_bcnt1_i32_b64 s16, s[6:7]
	s_cmp_gt_u32 s16, 15
	s_cselect_b32 s10, s11, s10
	s_or_b32 s11, s10, 0x80000
	v_cmp_le_u32_e64 s[6:7], s11, v18
	s_bcnt1_i32_b64 s16, s[6:7]
	s_cmp_gt_u32 s16, 15
	s_cselect_b32 s10, s11, s10
	s_or_b32 s11, s10, 0x40000
	v_cmp_le_u32_e64 s[6:7], s11, v18
	s_bcnt1_i32_b64 s16, s[6:7]
	s_cmp_gt_u32 s16, 15
	s_cselect_b32 s10, s11, s10
	s_or_b32 s11, s10, 0x20000
	v_cmp_le_u32_e64 s[6:7], s11, v18
	s_bcnt1_i32_b64 s16, s[6:7]
	s_cmp_gt_u32 s16, 15
	s_cselect_b32 s10, s11, s10
	s_or_b32 s11, s10, 0x10000
	v_cmp_le_u32_e64 s[6:7], s11, v18
	s_bcnt1_i32_b64 s16, s[6:7]
	s_cmp_gt_u32 s16, 15
	s_cselect_b32 s10, s11, s10
	s_or_b32 s11, s10, 0x8000
	v_cmp_le_u32_e64 s[6:7], s11, v18
	s_bcnt1_i32_b64 s16, s[6:7]
	s_cmp_gt_u32 s16, 15
	s_cselect_b32 s10, s11, s10
	s_or_b32 s11, s10, 0x4000
	v_cmp_le_u32_e64 s[6:7], s11, v18
	s_bcnt1_i32_b64 s16, s[6:7]
	s_cmp_gt_u32 s16, 15
	s_cselect_b32 s10, s11, s10
	s_or_b32 s11, s10, 0x2000
	v_cmp_le_u32_e64 s[6:7], s11, v18
	s_bcnt1_i32_b64 s16, s[6:7]
	s_cmp_gt_u32 s16, 15
	s_cselect_b32 s10, s11, s10
	s_or_b32 s11, s10, 0x1000
	v_cmp_le_u32_e64 s[6:7], s11, v18
	s_bcnt1_i32_b64 s16, s[6:7]
	s_cmp_gt_u32 s16, 15
	s_cselect_b32 s10, s11, s10
	s_or_b32 s11, s10, 0x800
	v_cmp_le_u32_e64 s[6:7], s11, v18
	s_bcnt1_i32_b64 s16, s[6:7]
	s_cmp_gt_u32 s16, 15
	s_cselect_b32 s10, s11, s10
	s_or_b32 s11, s10, 0x400
	v_cmp_le_u32_e64 s[6:7], s11, v18
	s_bcnt1_i32_b64 s16, s[6:7]
	s_cmp_gt_u32 s16, 15
	s_cselect_b32 s10, s11, s10
	s_or_b32 s11, s10, 0x200
	v_cmp_le_u32_e64 s[6:7], s11, v18
	s_bcnt1_i32_b64 s16, s[6:7]
	s_cmp_gt_u32 s16, 15
	s_cselect_b32 s10, s11, s10
	s_or_b32 s11, s10, 0x100
	v_cmp_le_u32_e64 s[6:7], s11, v18
	s_bcnt1_i32_b64 s16, s[6:7]
	s_cmp_gt_u32 s16, 15
	s_cselect_b32 s10, s11, s10
	s_or_b32 s11, s10, 0x80
	v_cmp_le_u32_e64 s[6:7], s11, v18
	s_bcnt1_i32_b64 s16, s[6:7]
	s_cmp_gt_u32 s16, 15
	s_cselect_b32 s10, s11, s10
	s_or_b32 s11, s10, 64
	v_cmp_le_u32_e64 s[6:7], s11, v18
	s_bcnt1_i32_b64 s16, s[6:7]
	s_cmp_gt_u32 s16, 15
	s_cselect_b32 s10, s11, s10
	s_or_b32 s11, s10, 32
	v_cmp_le_u32_e64 s[6:7], s11, v18
	s_bcnt1_i32_b64 s16, s[6:7]
	s_cmp_gt_u32 s16, 15
	s_cselect_b32 s10, s11, s10
	s_or_b32 s11, s10, 16
	v_cmp_le_u32_e64 s[6:7], s11, v18
	s_bcnt1_i32_b64 s16, s[6:7]
	s_cmp_gt_u32 s16, 15
	s_cselect_b32 s10, s11, s10
	s_or_b32 s11, s10, 8
	v_cmp_le_u32_e64 s[6:7], s11, v18
	s_bcnt1_i32_b64 s16, s[6:7]
	s_cmp_gt_u32 s16, 15
	s_cselect_b32 s10, s11, s10
	s_or_b32 s11, s10, 4
	v_cmp_le_u32_e64 s[6:7], s11, v18
	s_bcnt1_i32_b64 s16, s[6:7]
	s_cmp_gt_u32 s16, 15
	s_cselect_b32 s10, s11, s10
	s_or_b32 s11, s10, 2
	v_cmp_le_u32_e64 s[6:7], s11, v18
	s_bcnt1_i32_b64 s16, s[6:7]
	s_cmp_gt_u32 s16, 15
	s_cselect_b32 s10, s11, s10
	s_or_b32 s11, s10, 1
	v_cmp_le_u32_e64 s[6:7], s11, v18
	s_bcnt1_i32_b64 s16, s[6:7]
	s_cmp_gt_u32 s16, 15
	s_cselect_b32 s4, s11, s10
	v_cmp_eq_u32_e64 s[44:45], s4, v18
	v_cmp_ge_u32_e64 s[6:7], s4, v18
	v_cmp_lt_u32_e64 s[46:47], s4, v18
	s_and_saveexec_b64 s[10:11], s[6:7]
	s_cbranch_execz .LBB0_406
	s_bcnt1_i32_b64 s4, s[46:47]
	v_mbcnt_lo_u32_b32 v18, s44, 0
	s_sub_i32 s4, 16, s4
	v_mbcnt_hi_u32_b32 v18, s45, v18
	v_cmp_gt_i32_e64 s[6:7], s4, v18
	s_and_b64 s[4:5], s[44:45], s[6:7]
	s_and_b64 s[4:5], s[4:5], s[8:9]
	s_andn2_b64 s[6:7], s[8:9], exec
	s_and_b64 s[4:5], s[4:5], exec
	s_or_b64 s[22:23], s[6:7], s[4:5]
